# attention VALU budget per MFMA gap 20 instead of 24 (on v031)
# baseline (speedup 1.0000x reference)
; #define MFMA32(a, b, c) __builtin_amdgcn_mfma_f32_32x32x16_bf16((a), (b), (c), 0, 0, 0)
; DI void attn_item(const Ctx& c, int item, bf16* lds) {
;     ...
;         for (int mt = 0; mt < 2; ++mt)
; #pragma unroll
;           for (int s = 0; s < 6; ++s) {
;             const bf16x8 a = *(const bf16x8*)(Ks + (32 * mt + r) * AK_LD + 16 * s + 8 * hh);
;             const bf16x8 qb_ = (qs == 0) ? qf0[s] : *(const bf16x8*)(Qs + r * AK_LD + 16 * s + 8 * hh);
;             st[mt] = (s == 0) ? MFMA32(a, qb_, zz) : MFMA32(a, qb_, st[mt]);
;           }
;       }
;       if (__builtin_amdgcn_ballot_w64(m[qs] != 0.f) != 0ull) {
; #pragma unroll
;         for (int i = 0; i < 16; ++i) { st[0][i] -= m[qs]; st[1][i] -= m[qs]; }
;       }
;       float mx = st[0][0];
; #pragma unroll
;       for (int i = 1; i < 16; ++i) mx = fmaxf(mx, st[0][i]);
; #pragma unroll
;       for (int i = 0; i < 16; ++i) mx = fmaxf(mx, st[1][i]);
;       mx = xhalf_max(mx);
;       if (__builtin_amdgcn_ballot_w64((kt == 0) ? (fabsf(mx) > 16.f) : (mx > 16.f)) != 0ull) {
;         const float d = (kt == 0) ? mx : fmaxf(mx, 0.f);
;         const float alpha = __builtin_amdgcn_exp2f(-d);
;         m[qs] += d; lsum[qs] *= alpha;
; #pragma unroll
;         for (int i = 0; i < 16; ++i) { ot[qs][0][i] *= alpha; ot[qs][1][i] *= alpha; st[0][i] -= d; st[1][i] -= d; }
;       }
;       float ps = 0.f;
; #pragma unroll
;       for (int sp = 0; sp < 4; ++sp) {
;         const int mt = sp >> 1, s2 = sp & 1;
;         float e[8];
; #pragma unroll
;         for (int j = 0; j < 8; ++j) { e[j] = __builtin_amdgcn_exp2f(st[mt][8 * s2 + j]); ps += e[j]; }
;         u32x4 pk;
;         pk[0] = pk2(e[0], e[1]); pk[1] = pk2(e[2], e[3]); pk[2] = pk2(e[4], e[5]); pk[3] = pk2(e[6], e[7]);
;         const bf16x8 pf = __builtin_bit_cast(bf16x8, pk);
; #pragma unroll
;         for (int vt = 0; vt < 2; ++vt) {
;           const bf16* vp = Vs + (32 * vt + r) * AV_LD + 32 * mt + 16 * s2 + 4 * hh;
;           const s16x4 lo = *(const s16x4*)(vp), hi = *(const s16x4*)(vp + 8);
;           const bf16x8 a = __builtin_shufflevector(lo, hi, 0, 1, 2, 3, 4, 5, 6, 7);
;           ot[qs][vt] = MFMA32(a, pf, ot[qs][vt]);
;         }
;       }
;       lsum[qs] += ps;
.Lattn_00_A_nosub:
	v_max3_f32 v185, v80, v81, v82
	v_max3_f32 v185, v185, v83, v84
	v_max3_f32 v185, v185, v85, v86
	v_max3_f32 v185, v185, v87, v88
	ds_read_b64 v[8:9], v202 offset:17664
	ds_read_b64 v[10:11], v202 offset:17680
	v_mfma_f32_32x32x16_bf16 v[32:47], v[12:15], v[104:107], v[32:47]
	v_max3_f32 v185, v185, v89, v90
	v_max3_f32 v185, v185, v91, v92
	v_max3_f32 v185, v185, v93, v94
	v_max_f32_e32 v185, v185, v95
	v_cndmask_b32_e64 v191, v185, |v185|, s[4:5]
	v_cmp_lt_f32_e32 vcc, s33, v191
	s_cbranch_vccnz .Lattn_00_A_rare
.Lattn_00_A_back:
	ds_read_b64 v[12:13], v202 offset:13344
	ds_read_b64 v[14:15], v202 offset:13360
	v_mfma_f32_32x32x16_bf16 v[16:31], v[192:195], v[104:107], v[16:31]
	v_exp_f32_e32 v80, v80
	v_exp_f32_e32 v81, v81
	v_exp_f32_e32 v82, v82
	ds_read_b64 v[192:193], v202 offset:17696
	ds_read_b64 v[194:195], v202 offset:17712
	v_mfma_f32_32x32x16_bf16 v[96:111], v[204:207], v[228:231], 0
	v_exp_f32_e32 v83, v83
	v_exp_f32_e32 v84, v84
	v_exp_f32_e32 v85, v85
	ds_read_b128 v[204:207], v159 offset:6656
	v_mfma_f32_32x32x16_bf16 v[96:111], v[208:211], v[232:235], v[96:111]
	v_exp_f32_e32 v86, v86
	v_exp_f32_e32 v87, v87
	v_add_f32_e32 v0, v0, v80
	ds_read_b128 v[208:211], v159 offset:6688
	v_mfma_f32_32x32x16_bf16 v[96:111], v[212:215], v[236:239], v[96:111]
	v_add_f32_e32 v0, v0, v81
	v_add_f32_e32 v0, v0, v82
	v_add_f32_e32 v0, v0, v83
	v_add_f32_e32 v0, v0, v84
	v_add_f32_e32 v0, v0, v85
	ds_read_b128 v[212:215], v159 offset:6720
	v_mfma_f32_32x32x16_bf16 v[96:111], v[216:219], v[240:243], v[96:111]
	v_add_f32_e32 v0, v0, v86
	v_add_f32_e32 v0, v0, v87
	v_cvt_pk_bf16_f32 v80, v80, v81
	v_cvt_pk_bf16_f32 v81, v82, v83
	v_cvt_pk_bf16_f32 v82, v84, v85
	ds_read_b128 v[216:219], v159 offset:6752
	v_mfma_f32_32x32x16_bf16 v[96:111], v[220:223], v[244:247], v[96:111]
	v_cvt_pk_bf16_f32 v83, v86, v87
	v_exp_f32_e32 v88, v88
	v_exp_f32_e32 v89, v89
	ds_read_b128 v[220:223], v159 offset:6784
	v_mfma_f32_32x32x16_bf16 v[96:111], v[224:227], v[248:251], v[96:111]
	v_exp_f32_e32 v90, v90
	v_exp_f32_e32 v91, v91
	v_exp_f32_e32 v92, v92
	ds_read_b128 v[224:227], v159 offset:6816
	s_waitcnt lgkmcnt(12)
	v_mfma_f32_32x32x16_bf16 v[64:79], v[4:7], v[80:83], v[64:79]
	v_exp_f32_e32 v93, v93
	v_exp_f32_e32 v94, v94
	v_exp_f32_e32 v95, v95
	s_waitcnt vmcnt(0)
	ds_write_b128 v3, v[136:139] offset:22016
	s_waitcnt lgkmcnt(11)
	v_mfma_f32_32x32x16_bf16 v[48:63], v[8:11], v[80:83], v[48:63]
	v_add_f32_e32 v0, v0, v88
	v_add_f32_e32 v0, v0, v89
	v_add_f32_e32 v0, v0, v90
	v_add_f32_e32 v0, v0, v91
	v_add_f32_e32 v0, v0, v92
	ds_write_b128 v161, v[140:143] offset:22016
	s_waitcnt lgkmcnt(10)
	v_add_f32_e32 v0, v0, v93
	v_add_f32_e32 v0, v0, v94
	v_add_f32_e32 v0, v0, v95
	v_cvt_pk_bf16_f32 v88, v88, v89
	v_cvt_pk_bf16_f32 v89, v90, v91
	v_cvt_pk_bf16_f32 v90, v92, v93
	v_cvt_pk_bf16_f32 v91, v94, v95
	s_nop 1
	v_mfma_f32_32x32x16_bf16 v[64:79], v[12:15], v[88:91], v[64:79]
	s_cmp_eq_u32 s12, 0
	s_cbranch_scc1 .Lattn_00_B_nosub
	v_sub_f32_e32 v96, v96, v201
	v_sub_f32_e32 v97, v97, v201
	v_sub_f32_e32 v98, v98, v201
	v_sub_f32_e32 v99, v99, v201
	v_sub_f32_e32 v100, v100, v201
	v_sub_f32_e32 v101, v101, v201
	v_sub_f32_e32 v102, v102, v201
	v_sub_f32_e32 v103, v103, v201
	v_sub_f32_e32 v104, v104, v201
	v_sub_f32_e32 v105, v105, v201
	v_sub_f32_e32 v106, v106, v201
	v_sub_f32_e32 v107, v107, v201
	v_sub_f32_e32 v108, v108, v201
	v_sub_f32_e32 v109, v109, v201
	v_sub_f32_e32 v110, v110, v201
	v_sub_f32_e32 v111, v111, v201
.Lattn_00_B_nosub:
	v_max3_f32 v185, v96, v97, v98
	v_max3_f32 v185, v185, v99, v100
	v_max3_f32 v185, v185, v101, v102
	v_max3_f32 v185, v185, v103, v104
	ds_write_b128 v182, v[144:147] offset:22016
	s_waitcnt lgkmcnt(9)
	v_mfma_f32_32x32x16_bf16 v[48:63], v[192:195], v[88:91], v[48:63]
	v_max3_f32 v185, v185, v105, v106
	v_max3_f32 v185, v185, v107, v108
	v_max3_f32 v185, v185, v109, v110
	v_max_f32_e32 v185, v185, v111
	v_cndmask_b32_e64 v191, v185, |v185|, s[4:5]
	v_cmp_lt_f32_e32 vcc, s33, v191
	s_cbranch_vccnz .Lattn_00_B_rare
.Lattn_00_B_back:
	ds_write_b64 v184, v[148:149] offset:35328
	ds_write_b64 v184, v[150:151] offset:35336
	s_waitcnt lgkmcnt(10)
	v_mfma_f32_32x32x16_bf16 v[80:95], v[204:207], v[112:115], 0
	v_exp_f32_e32 v96, v96
	v_exp_f32_e32 v97, v97
	v_exp_f32_e32 v98, v98
	ds_write_b64 v184, v[152:153] offset:39680
	ds_write_b64 v184, v[154:155] offset:39688
	s_waitcnt lgkmcnt(11)
	v_mfma_f32_32x32x16_bf16 v[80:95], v[208:211], v[116:119], v[80:95]
	v_exp_f32_e32 v99, v99
	v_exp_f32_e32 v100, v100
	v_exp_f32_e32 v101, v101
	global_load_dwordx4 v[136:139], v166, s[10:11]
	global_load_dwordx4 v[140:143], v168, s[10:11]
	global_load_dwordx4 v[144:147], v170, s[10:11]
	global_load_dwordx4 v[148:151], v162, s[2:3]
	global_load_dwordx4 v[152:155], v164, s[2:3]
	s_add_u32 s10, s10, 0x3000
	s_addc_u32 s11, s11, 0
	s_add_u32 s2, s2, 0x80
	s_addc_u32 s3, s3, 0
	s_waitcnt lgkmcnt(10)
	v_mfma_f32_32x32x16_bf16 v[80:95], v[212:215], v[120:123], v[80:95]
	v_exp_f32_e32 v102, v102
	v_exp_f32_e32 v103, v103
	v_add_f32_e32 v203, v203, v96
	s_waitcnt lgkmcnt(9)
	v_mfma_f32_32x32x16_bf16 v[80:95], v[216:219], v[124:127], v[80:95]
	v_add_f32_e32 v203, v203, v97
	v_add_f32_e32 v203, v203, v98
	v_add_f32_e32 v203, v203, v99
	v_add_f32_e32 v203, v203, v100
	v_add_f32_e32 v203, v203, v101
	s_waitcnt lgkmcnt(8)
	v_mfma_f32_32x32x16_bf16 v[80:95], v[220:223], v[128:131], v[80:95]
	v_add_f32_e32 v203, v203, v102
	v_add_f32_e32 v203, v203, v103
	v_cvt_pk_bf16_f32 v96, v96, v97
	v_cvt_pk_bf16_f32 v97, v98, v99
	v_cvt_pk_bf16_f32 v98, v100, v101
	s_waitcnt lgkmcnt(7)
	v_mfma_f32_32x32x16_bf16 v[80:95], v[224:227], v[132:135], v[80:95]
	v_cvt_pk_bf16_f32 v99, v102, v103
	v_exp_f32_e32 v104, v104
	v_exp_f32_e32 v105, v105
	s_waitcnt lgkmcnt(0)
	s_barrier
; #define MFMA32(a, b, c) __builtin_amdgcn_mfma_f32_32x32x16_bf16((a), (b), (c), 0, 0, 0)
; DI void attn_item(const Ctx& c, int item, bf16* lds) {
;     ...
;         for (int mt = 0; mt < 2; ++mt)
; #pragma unroll
;           for (int s = 0; s < 6; ++s) {
;             const bf16x8 a = *(const bf16x8*)(Ks + (32 * mt + r) * AK_LD + 16 * s + 8 * hh);
;             const bf16x8 qb_ = (qs == 0) ? qf0[s] : *(const bf16x8*)(Qs + r * AK_LD + 16 * s + 8 * hh);
;             st[mt] = (s == 0) ? MFMA32(a, qb_, zz) : MFMA32(a, qb_, st[mt]);
;           }
;       }
;       if (__builtin_amdgcn_ballot_w64(m[qs] != 0.f) != 0ull) {
; #pragma unroll
;         for (int i = 0; i < 16; ++i) { st[0][i] -= m[qs]; st[1][i] -= m[qs]; }
;       }
;       float mx = st[0][0];
; #pragma unroll
;       for (int i = 1; i < 16; ++i) mx = fmaxf(mx, st[0][i]);
; #pragma unroll
;       for (int i = 0; i < 16; ++i) mx = fmaxf(mx, st[1][i]);
;       mx = xhalf_max(mx);
;       if (__builtin_amdgcn_ballot_w64((kt == 0) ? (fabsf(mx) > 16.f) : (mx > 16.f)) != 0ull) {
;         const float d = (kt == 0) ? mx : fmaxf(mx, 0.f);
;         const float alpha = __builtin_amdgcn_exp2f(-d);
;         m[qs] += d; lsum[qs] *= alpha;
; #pragma unroll
;         for (int i = 0; i < 16; ++i) { ot[qs][0][i] *= alpha; ot[qs][1][i] *= alpha; st[0][i] -= d; st[1][i] -= d; }
;       }
;       float ps = 0.f;
; #pragma unroll
;       for (int sp = 0; sp < 4; ++sp) {
;         const int mt = sp >> 1, s2 = sp & 1;
;         float e[8];
; #pragma unroll
;         for (int j = 0; j < 8; ++j) { e[j] = __builtin_amdgcn_exp2f(st[mt][8 * s2 + j]); ps += e[j]; }
;         u32x4 pk;
;         pk[0] = pk2(e[0], e[1]); pk[1] = pk2(e[2], e[3]); pk[2] = pk2(e[4], e[5]); pk[3] = pk2(e[6], e[7]);
;         const bf16x8 pf = __builtin_bit_cast(bf16x8, pk);
; #pragma unroll
;         for (int vt = 0; vt < 2; ++vt) {
;           const bf16* vp = Vs + (32 * vt + r) * AV_LD + 32 * mt + 16 * s2 + 4 * hh;
;           const s16x4 lo = *(const s16x4*)(vp), hi = *(const s16x4*)(vp + 8);
;           const bf16x8 a = __builtin_shufflevector(lo, hi, 0, 1, 2, 3, 4, 5, 6, 7);
;           ot[qs][vt] = MFMA32(a, pf, ot[qs][vt]);
;         }
;       }
;       lsum[qs] += ps;
	v_mfma_f32_32x32x16_bf16 v[32:47], v[4:7], v[96:99], v[32:47]
	v_exp_f32_e32 v106, v106
	v_exp_f32_e32 v107, v107
	v_exp_f32_e32 v108, v108
	ds_read_b64 v[4:5], v202 offset:13376
	ds_read_b64 v[6:7], v202 offset:13392
	v_mfma_f32_32x32x16_bf16 v[16:31], v[8:11], v[96:99], v[16:31]
	v_exp_f32_e32 v109, v109
	v_exp_f32_e32 v110, v110
	v_exp_f32_e32 v111, v111
	ds_read_b64 v[8:9], v202 offset:17728
	ds_read_b64 v[10:11], v202 offset:17744
	v_add_f32_e32 v203, v203, v104
	v_add_f32_e32 v203, v203, v105
	v_add_f32_e32 v203, v203, v106
	v_add_f32_e32 v203, v203, v107
	v_add_f32_e32 v203, v203, v108
	v_add_f32_e32 v203, v203, v109
	v_add_f32_e32 v203, v203, v110
	v_add_f32_e32 v203, v203, v111
	v_cvt_pk_bf16_f32 v104, v104, v105
	v_cvt_pk_bf16_f32 v105, v106, v107
	v_cvt_pk_bf16_f32 v106, v108, v109
	v_cvt_pk_bf16_f32 v107, v110, v111
	s_nop 1
	v_mfma_f32_32x32x16_bf16 v[32:47], v[12:15], v[104:107], v[32:47]
	s_cmp_eq_u32 s9, 0
	s_cbranch_scc1 .Lattn_01_A_nosub
	v_sub_f32_e32 v80, v80, v2
	v_sub_f32_e32 v81, v81, v2
	v_sub_f32_e32 v82, v82, v2
	v_sub_f32_e32 v83, v83, v2
	v_sub_f32_e32 v84, v84, v2
	v_sub_f32_e32 v85, v85, v2
	v_sub_f32_e32 v86, v86, v2
	v_sub_f32_e32 v87, v87, v2
	v_sub_f32_e32 v88, v88, v2
	v_sub_f32_e32 v89, v89, v2
	v_sub_f32_e32 v90, v90, v2
	v_sub_f32_e32 v91, v91, v2
	v_sub_f32_e32 v92, v92, v2
	v_sub_f32_e32 v93, v93, v2
	v_sub_f32_e32 v94, v94, v2
	v_sub_f32_e32 v95, v95, v2
.Lattn_01_A_nosub:
	v_max3_f32 v185, v80, v81, v82
	v_max3_f32 v185, v185, v83, v84
	v_max3_f32 v185, v185, v85, v86
	v_max3_f32 v185, v185, v87, v88
	ds_read_b64 v[12:13], v202 offset:13408
	ds_read_b64 v[14:15], v202 offset:13424
	v_mfma_f32_32x32x16_bf16 v[16:31], v[192:195], v[104:107], v[16:31]
	v_max3_f32 v185, v185, v89, v90
	v_max3_f32 v185, v185, v91, v92
	v_max3_f32 v185, v185, v93, v94
	v_max_f32_e32 v185, v185, v95
	v_cmp_lt_f32_e32 vcc, s33, v185
	s_cbranch_vccnz .Lattn_01_A_rare
.Lattn_01_A_back:
	ds_read_b64 v[192:193], v202 offset:17760
	ds_read_b64 v[194:195], v202 offset:17776
	v_mfma_f32_32x32x16_bf16 v[96:111], v[204:207], v[228:231], 0
	v_exp_f32_e32 v80, v80
	v_exp_f32_e32 v81, v81
	v_exp_f32_e32 v82, v82
	ds_read_b128 v[204:207], v159 offset:22016
	v_mfma_f32_32x32x16_bf16 v[96:111], v[208:211], v[232:235], v[96:111]
	v_exp_f32_e32 v83, v83
	v_exp_f32_e32 v84, v84
	v_exp_f32_e32 v85, v85
	ds_read_b128 v[208:211], v159 offset:22048
	v_mfma_f32_32x32x16_bf16 v[96:111], v[212:215], v[236:239], v[96:111]
	v_exp_f32_e32 v86, v86
	v_exp_f32_e32 v87, v87
	v_add_f32_e32 v0, v0, v80
	ds_read_b128 v[212:215], v159 offset:22080
	v_mfma_f32_32x32x16_bf16 v[96:111], v[216:219], v[240:243], v[96:111]
	v_add_f32_e32 v0, v0, v81
	v_add_f32_e32 v0, v0, v82
	v_add_f32_e32 v0, v0, v83
	v_add_f32_e32 v0, v0, v84
	v_add_f32_e32 v0, v0, v85
	ds_read_b128 v[216:219], v159 offset:22112
	v_mfma_f32_32x32x16_bf16 v[96:111], v[220:223], v[244:247], v[96:111]
	v_add_f32_e32 v0, v0, v86
	v_add_f32_e32 v0, v0, v87
	v_cvt_pk_bf16_f32 v80, v80, v81
	v_cvt_pk_bf16_f32 v81, v82, v83
	v_cvt_pk_bf16_f32 v82, v84, v85
	ds_read_b128 v[220:223], v159 offset:22144
	v_mfma_f32_32x32x16_bf16 v[96:111], v[224:227], v[248:251], v[96:111]
	v_cvt_pk_bf16_f32 v83, v86, v87
	v_exp_f32_e32 v88, v88
	v_exp_f32_e32 v89, v89
	ds_read_b128 v[224:227], v159 offset:22176
	s_waitcnt lgkmcnt(12)
	v_mfma_f32_32x32x16_bf16 v[64:79], v[4:7], v[80:83], v[64:79]
	v_exp_f32_e32 v90, v90
	v_exp_f32_e32 v91, v91
	v_exp_f32_e32 v92, v92
	s_waitcnt lgkmcnt(10)
	v_mfma_f32_32x32x16_bf16 v[48:63], v[8:11], v[80:83], v[48:63]
	v_exp_f32_e32 v93, v93
	v_exp_f32_e32 v94, v94
	v_exp_f32_e32 v95, v95
	s_waitcnt lgkmcnt(8)
	v_add_f32_e32 v0, v0, v88
	v_add_f32_e32 v0, v0, v89
	v_add_f32_e32 v0, v0, v90
	v_add_f32_e32 v0, v0, v91
	v_add_f32_e32 v0, v0, v92
	v_add_f32_e32 v0, v0, v93
	v_add_f32_e32 v0, v0, v94
	v_add_f32_e32 v0, v0, v95
	v_cvt_pk_bf16_f32 v88, v88, v89
	v_cvt_pk_bf16_f32 v89, v90, v91
	v_cvt_pk_bf16_f32 v90, v92, v93
	v_cvt_pk_bf16_f32 v91, v94, v95
	s_nop 1
	v_mfma_f32_32x32x16_bf16 v[64:79], v[12:15], v[88:91], v[64:79]
	s_cmp_eq_u32 s12, 0
	s_cbranch_scc1 .Lattn_01_B_nosub
	v_sub_f32_e32 v96, v96, v201
	v_sub_f32_e32 v97, v97, v201
	v_sub_f32_e32 v98, v98, v201
	v_sub_f32_e32 v99, v99, v201
	v_sub_f32_e32 v100, v100, v201
	v_sub_f32_e32 v101, v101, v201
	v_sub_f32_e32 v102, v102, v201
	v_sub_f32_e32 v103, v103, v201
	v_sub_f32_e32 v104, v104, v201
	v_sub_f32_e32 v105, v105, v201
	v_sub_f32_e32 v106, v106, v201
	v_sub_f32_e32 v107, v107, v201
	v_sub_f32_e32 v108, v108, v201
	v_sub_f32_e32 v109, v109, v201
	v_sub_f32_e32 v110, v110, v201
	v_sub_f32_e32 v111, v111, v201
.Lattn_01_B_nosub:
	v_max3_f32 v185, v96, v97, v98
	v_max3_f32 v185, v185, v99, v100
	v_max3_f32 v185, v185, v101, v102
	v_max3_f32 v185, v185, v103, v104
	s_waitcnt lgkmcnt(6)
	v_mfma_f32_32x32x16_bf16 v[48:63], v[192:195], v[88:91], v[48:63]
	v_max3_f32 v185, v185, v105, v106
	v_max3_f32 v185, v185, v107, v108
	v_max3_f32 v185, v185, v109, v110
	v_max_f32_e32 v185, v185, v111
	v_cmp_lt_f32_e32 vcc, s33, v185
	s_cbranch_vccnz .Lattn_01_B_rare
; #define MFMA32(a, b, c) __builtin_amdgcn_mfma_f32_32x32x16_bf16((a), (b), (c), 0, 0, 0)
; DI void attn_item(const Ctx& c, int item, bf16* lds) {
;     ...
;         for (int mt = 0; mt < 2; ++mt)
; #pragma unroll
;           for (int s = 0; s < 6; ++s) {
;             const bf16x8 a = *(const bf16x8*)(Ks + (32 * mt + r) * AK_LD + 16 * s + 8 * hh);
;             const bf16x8 qb_ = (qs == 0) ? qf0[s] : *(const bf16x8*)(Qs + r * AK_LD + 16 * s + 8 * hh);
;             st[mt] = (s == 0) ? MFMA32(a, qb_, zz) : MFMA32(a, qb_, st[mt]);
;           }
;       }
;       if (__builtin_amdgcn_ballot_w64(m[qs] != 0.f) != 0ull) {
; #pragma unroll
;         for (int i = 0; i < 16; ++i) { st[0][i] -= m[qs]; st[1][i] -= m[qs]; }
;       }
;       float mx = st[0][0];
; #pragma unroll
;       for (int i = 1; i < 16; ++i) mx = fmaxf(mx, st[0][i]);
; #pragma unroll
;       for (int i = 0; i < 16; ++i) mx = fmaxf(mx, st[1][i]);
;       mx = xhalf_max(mx);
;       if (__builtin_amdgcn_ballot_w64((kt == 0) ? (fabsf(mx) > 16.f) : (mx > 16.f)) != 0ull) {
;         const float d = (kt == 0) ? mx : fmaxf(mx, 0.f);
;         const float alpha = __builtin_amdgcn_exp2f(-d);
;         m[qs] += d; lsum[qs] *= alpha;
; #pragma unroll
;         for (int i = 0; i < 16; ++i) { ot[qs][0][i] *= alpha; ot[qs][1][i] *= alpha; st[0][i] -= d; st[1][i] -= d; }
;       }
;       float ps = 0.f;
; #pragma unroll
;       for (int sp = 0; sp < 4; ++sp) {
;         const int mt = sp >> 1, s2 = sp & 1;
;         float e[8];
; #pragma unroll
;         for (int j = 0; j < 8; ++j) { e[j] = __builtin_amdgcn_exp2f(st[mt][8 * s2 + j]); ps += e[j]; }
;         u32x4 pk;
;         pk[0] = pk2(e[0], e[1]); pk[1] = pk2(e[2], e[3]); pk[2] = pk2(e[4], e[5]); pk[3] = pk2(e[6], e[7]);
;         const bf16x8 pf = __builtin_bit_cast(bf16x8, pk);
; #pragma unroll
;         for (int vt = 0; vt < 2; ++vt) {
;           const bf16* vp = Vs + (32 * vt + r) * AV_LD + 32 * mt + 16 * s2 + 4 * hh;
;           const s16x4 lo = *(const s16x4*)(vp), hi = *(const s16x4*)(vp + 8);
;           const bf16x8 a = __builtin_shufflevector(lo, hi, 0, 1, 2, 3, 4, 5, 6, 7);
;           ot[qs][vt] = MFMA32(a, pf, ot[qs][vt]);
;         }
;       }
;       lsum[qs] += ps;
.Lattn_01_B_back:
	s_waitcnt lgkmcnt(5)
	v_mfma_f32_32x32x16_bf16 v[80:95], v[204:207], v[112:115], 0
	v_exp_f32_e32 v96, v96
	v_exp_f32_e32 v97, v97
	v_exp_f32_e32 v98, v98
	s_waitcnt lgkmcnt(4)
	v_mfma_f32_32x32x16_bf16 v[80:95], v[208:211], v[116:119], v[80:95]
	v_exp_f32_e32 v99, v99
	v_exp_f32_e32 v100, v100
	v_exp_f32_e32 v101, v101
	s_waitcnt lgkmcnt(3)
	v_mfma_f32_32x32x16_bf16 v[80:95], v[212:215], v[120:123], v[80:95]
	v_exp_f32_e32 v102, v102
	v_exp_f32_e32 v103, v103
	v_add_f32_e32 v203, v203, v96
	s_waitcnt lgkmcnt(2)
	v_mfma_f32_32x32x16_bf16 v[80:95], v[216:219], v[124:127], v[80:95]
	v_add_f32_e32 v203, v203, v97
	v_add_f32_e32 v203, v203, v98
	v_add_f32_e32 v203, v203, v99
	v_add_f32_e32 v203, v203, v100
	v_add_f32_e32 v203, v203, v101
	s_waitcnt lgkmcnt(1)
	v_mfma_f32_32x32x16_bf16 v[80:95], v[220:223], v[128:131], v[80:95]
	v_add_f32_e32 v203, v203, v102
	v_add_f32_e32 v203, v203, v103
	v_cvt_pk_bf16_f32 v96, v96, v97
	v_cvt_pk_bf16_f32 v97, v98, v99
	v_cvt_pk_bf16_f32 v98, v100, v101
	s_waitcnt lgkmcnt(0)
	v_mfma_f32_32x32x16_bf16 v[80:95], v[224:227], v[132:135], v[80:95]
	v_cvt_pk_bf16_f32 v99, v102, v103
	v_exp_f32_e32 v104, v104
	v_exp_f32_e32 v105, v105
	s_add_i32 s1, s1, 1
	v_mfma_f32_32x32x16_bf16 v[32:47], v[4:7], v[96:99], v[32:47]
	v_exp_f32_e32 v106, v106
	v_exp_f32_e32 v107, v107
	v_exp_f32_e32 v108, v108
	ds_read_b64 v[4:5], v202 offset:35328
	ds_read_b64 v[6:7], v202 offset:35344
	v_mfma_f32_32x32x16_bf16 v[16:31], v[8:11], v[96:99], v[16:31]
	v_exp_f32_e32 v109, v109
	v_exp_f32_e32 v110, v110
	v_exp_f32_e32 v111, v111
	ds_read_b64 v[8:9], v202 offset:39680
	ds_read_b64 v[10:11], v202 offset:39696
	v_add_f32_e32 v203, v203, v104
	v_add_f32_e32 v203, v203, v105
	v_add_f32_e32 v203, v203, v106
	v_add_f32_e32 v203, v203, v107
	v_add_f32_e32 v203, v203, v108
	v_add_f32_e32 v203, v203, v109
	v_add_f32_e32 v203, v203, v110
	v_add_f32_e32 v203, v203, v111
	v_cvt_pk_bf16_f32 v104, v104, v105
	v_cvt_pk_bf16_f32 v105, v106, v107
	v_cvt_pk_bf16_f32 v106, v108, v109
	v_cvt_pk_bf16_f32 v107, v110, v111
	s_nop 1
	v_mfma_f32_32x32x16_bf16 v[32:47], v[12:15], v[104:107], v[32:47]
	s_cmp_eq_u32 s9, 0
	s_cbranch_scc1 .Lattn_10_A_nosub
	v_sub_f32_e32 v80, v80, v2
	v_sub_f32_e32 v81, v81, v2
	v_sub_f32_e32 v82, v82, v2
	v_sub_f32_e32 v83, v83, v2
	v_sub_f32_e32 v84, v84, v2
	v_sub_f32_e32 v85, v85, v2
	v_sub_f32_e32 v86, v86, v2
	v_sub_f32_e32 v87, v87, v2
	v_sub_f32_e32 v88, v88, v2
	v_sub_f32_e32 v89, v89, v2
	v_sub_f32_e32 v90, v90, v2
	v_sub_f32_e32 v91, v91, v2
	v_sub_f32_e32 v92, v92, v2
	v_sub_f32_e32 v93, v93, v2
	v_sub_f32_e32 v94, v94, v2
	v_sub_f32_e32 v95, v95, v2
.Lattn_10_A_nosub:
	v_max3_f32 v185, v80, v81, v82
	v_max3_f32 v185, v185, v83, v84
	v_max3_f32 v185, v185, v85, v86
	v_max3_f32 v185, v185, v87, v88
	ds_read_b64 v[12:13], v202 offset:35360
	ds_read_b64 v[14:15], v202 offset:35376
	v_mfma_f32_32x32x16_bf16 v[16:31], v[192:195], v[104:107], v[16:31]
	v_max3_f32 v185, v185, v89, v90
	v_max3_f32 v185, v185, v91, v92
	v_max3_f32 v185, v185, v93, v94
	v_max_f32_e32 v185, v185, v95
	v_cmp_lt_f32_e32 vcc, s33, v185
	s_cbranch_vccnz .Lattn_10_A_rare
.Lattn_10_A_back:
	ds_read_b64 v[192:193], v202 offset:39712
	ds_read_b64 v[194:195], v202 offset:39728
	v_mfma_f32_32x32x16_bf16 v[96:111], v[204:207], v[228:231], 0
	v_exp_f32_e32 v80, v80
	v_exp_f32_e32 v81, v81
	v_exp_f32_e32 v82, v82
	ds_read_b128 v[204:207], v159 offset:28672
	v_mfma_f32_32x32x16_bf16 v[96:111], v[208:211], v[232:235], v[96:111]
	v_exp_f32_e32 v83, v83
	v_exp_f32_e32 v84, v84
	v_exp_f32_e32 v85, v85
	ds_read_b128 v[208:211], v159 offset:28704
	v_mfma_f32_32x32x16_bf16 v[96:111], v[212:215], v[236:239], v[96:111]
	v_exp_f32_e32 v86, v86
	v_exp_f32_e32 v87, v87
	v_add_f32_e32 v0, v0, v80
	ds_read_b128 v[212:215], v159 offset:28736
	v_mfma_f32_32x32x16_bf16 v[96:111], v[216:219], v[240:243], v[96:111]
	v_add_f32_e32 v0, v0, v81
	v_add_f32_e32 v0, v0, v82
	v_add_f32_e32 v0, v0, v83
	v_add_f32_e32 v0, v0, v84
	v_add_f32_e32 v0, v0, v85
	ds_read_b128 v[216:219], v159 offset:28768
	v_mfma_f32_32x32x16_bf16 v[96:111], v[220:223], v[244:247], v[96:111]
	v_add_f32_e32 v0, v0, v86
	v_add_f32_e32 v0, v0, v87
	v_cvt_pk_bf16_f32 v80, v80, v81
	v_cvt_pk_bf16_f32 v81, v82, v83
	v_cvt_pk_bf16_f32 v82, v84, v85
	ds_read_b128 v[220:223], v159 offset:28800
	v_mfma_f32_32x32x16_bf16 v[96:111], v[224:227], v[248:251], v[96:111]
	v_cvt_pk_bf16_f32 v83, v86, v87
	v_exp_f32_e32 v88, v88
	v_exp_f32_e32 v89, v89
	ds_read_b128 v[224:227], v159 offset:28832
	s_waitcnt lgkmcnt(12)
	v_mfma_f32_32x32x16_bf16 v[64:79], v[4:7], v[80:83], v[64:79]
	v_exp_f32_e32 v90, v90
	v_exp_f32_e32 v91, v91
	v_exp_f32_e32 v92, v92
	s_waitcnt vmcnt(0)
	ds_write_b128 v3, v[136:139] offset:44032
	s_waitcnt lgkmcnt(11)
	v_mfma_f32_32x32x16_bf16 v[48:63], v[8:11], v[80:83], v[48:63]
	v_exp_f32_e32 v93, v93
	v_exp_f32_e32 v94, v94
	v_exp_f32_e32 v95, v95
	ds_write_b128 v161, v[140:143] offset:44032
	s_waitcnt lgkmcnt(10)
	v_add_f32_e32 v0, v0, v88
	v_add_f32_e32 v0, v0, v89
	v_add_f32_e32 v0, v0, v90
	v_add_f32_e32 v0, v0, v91
	v_add_f32_e32 v0, v0, v92
	v_add_f32_e32 v0, v0, v93
	v_add_f32_e32 v0, v0, v94
	v_add_f32_e32 v0, v0, v95
	v_cvt_pk_bf16_f32 v88, v88, v89
	v_cvt_pk_bf16_f32 v89, v90, v91
	v_cvt_pk_bf16_f32 v90, v92, v93
	v_cvt_pk_bf16_f32 v91, v94, v95
	s_nop 1
	v_mfma_f32_32x32x16_bf16 v[64:79], v[12:15], v[88:91], v[64:79]
	s_cmp_eq_u32 s12, 0
	s_cbranch_scc1 .Lattn_10_B_nosub
	v_sub_f32_e32 v96, v96, v201
	v_sub_f32_e32 v97, v97, v201
	v_sub_f32_e32 v98, v98, v201
	v_sub_f32_e32 v99, v99, v201
	v_sub_f32_e32 v100, v100, v201
	v_sub_f32_e32 v101, v101, v201
	v_sub_f32_e32 v102, v102, v201
	v_sub_f32_e32 v103, v103, v201
	v_sub_f32_e32 v104, v104, v201
	v_sub_f32_e32 v105, v105, v201
	v_sub_f32_e32 v106, v106, v201
	v_sub_f32_e32 v107, v107, v201
	v_sub_f32_e32 v108, v108, v201
	v_sub_f32_e32 v109, v109, v201
	v_sub_f32_e32 v110, v110, v201
	v_sub_f32_e32 v111, v111, v201
; #define MFMA32(a, b, c) __builtin_amdgcn_mfma_f32_32x32x16_bf16((a), (b), (c), 0, 0, 0)
; DI void attn_item(const Ctx& c, int item, bf16* lds) {
;     ...
;         for (int mt = 0; mt < 2; ++mt)
; #pragma unroll
;           for (int s = 0; s < 6; ++s) {
;             const bf16x8 a = *(const bf16x8*)(Ks + (32 * mt + r) * AK_LD + 16 * s + 8 * hh);
;             const bf16x8 qb_ = (qs == 0) ? qf0[s] : *(const bf16x8*)(Qs + r * AK_LD + 16 * s + 8 * hh);
;             st[mt] = (s == 0) ? MFMA32(a, qb_, zz) : MFMA32(a, qb_, st[mt]);
;           }
;       }
;       if (__builtin_amdgcn_ballot_w64(m[qs] != 0.f) != 0ull) {
; #pragma unroll
;         for (int i = 0; i < 16; ++i) { st[0][i] -= m[qs]; st[1][i] -= m[qs]; }
;       }
;       float mx = st[0][0];
; #pragma unroll
;       for (int i = 1; i < 16; ++i) mx = fmaxf(mx, st[0][i]);
; #pragma unroll
;       for (int i = 0; i < 16; ++i) mx = fmaxf(mx, st[1][i]);
;       mx = xhalf_max(mx);
;       if (__builtin_amdgcn_ballot_w64((kt == 0) ? (fabsf(mx) > 16.f) : (mx > 16.f)) != 0ull) {
;         const float d = (kt == 0) ? mx : fmaxf(mx, 0.f);
;         const float alpha = __builtin_amdgcn_exp2f(-d);
;         m[qs] += d; lsum[qs] *= alpha;
; #pragma unroll
;         for (int i = 0; i < 16; ++i) { ot[qs][0][i] *= alpha; ot[qs][1][i] *= alpha; st[0][i] -= d; st[1][i] -= d; }
;       }
;       float ps = 0.f;
; #pragma unroll
;       for (int sp = 0; sp < 4; ++sp) {
;         const int mt = sp >> 1, s2 = sp & 1;
;         float e[8];
; #pragma unroll
;         for (int j = 0; j < 8; ++j) { e[j] = __builtin_amdgcn_exp2f(st[mt][8 * s2 + j]); ps += e[j]; }
;         u32x4 pk;
;         pk[0] = pk2(e[0], e[1]); pk[1] = pk2(e[2], e[3]); pk[2] = pk2(e[4], e[5]); pk[3] = pk2(e[6], e[7]);
;         const bf16x8 pf = __builtin_bit_cast(bf16x8, pk);
; #pragma unroll
;         for (int vt = 0; vt < 2; ++vt) {
;           const bf16* vp = Vs + (32 * vt + r) * AV_LD + 32 * mt + 16 * s2 + 4 * hh;
;           const s16x4 lo = *(const s16x4*)(vp), hi = *(const s16x4*)(vp + 8);
;           const bf16x8 a = __builtin_shufflevector(lo, hi, 0, 1, 2, 3, 4, 5, 6, 7);
;           ot[qs][vt] = MFMA32(a, pf, ot[qs][vt]);
;         }
;       }
;       lsum[qs] += ps;
.Lattn_10_B_nosub:
	v_max3_f32 v185, v96, v97, v98
	v_max3_f32 v185, v185, v99, v100
	v_max3_f32 v185, v185, v101, v102
	v_max3_f32 v185, v185, v103, v104
	ds_write_b128 v182, v[144:147] offset:44032
	s_waitcnt lgkmcnt(9)
	v_mfma_f32_32x32x16_bf16 v[48:63], v[192:195], v[88:91], v[48:63]
	v_max3_f32 v185, v185, v105, v106
	v_max3_f32 v185, v185, v107, v108
	v_max3_f32 v185, v185, v109, v110
	v_max_f32_e32 v185, v185, v111
	v_cmp_lt_f32_e32 vcc, s33, v185
	s_cbranch_vccnz .Lattn_10_B_rare
.Lattn_10_B_back:
	ds_write_b64 v184, v[148:149] offset:57344
	ds_write_b64 v184, v[150:151] offset:57352
	s_waitcnt lgkmcnt(10)
	v_mfma_f32_32x32x16_bf16 v[80:95], v[204:207], v[112:115], 0
	v_exp_f32_e32 v96, v96
	v_exp_f32_e32 v97, v97
	v_exp_f32_e32 v98, v98
	ds_write_b64 v184, v[152:153] offset:61696
	ds_write_b64 v184, v[154:155] offset:61704
	s_waitcnt lgkmcnt(11)
	v_mfma_f32_32x32x16_bf16 v[80:95], v[208:211], v[116:119], v[80:95]
	v_exp_f32_e32 v99, v99
	v_exp_f32_e32 v100, v100
	v_exp_f32_e32 v101, v101
	global_load_dwordx4 v[136:139], v166, s[10:11]
	global_load_dwordx4 v[140:143], v168, s[10:11]
	global_load_dwordx4 v[144:147], v170, s[10:11]
	global_load_dwordx4 v[148:151], v162, s[2:3]
	global_load_dwordx4 v[152:155], v164, s[2:3]
	s_add_u32 s10, s10, 0x3000
	s_addc_u32 s11, s11, 0
	s_add_u32 s2, s2, 0x80
	s_addc_u32 s3, s3, 0
	s_waitcnt lgkmcnt(10)
	v_mfma_f32_32x32x16_bf16 v[80:95], v[212:215], v[120:123], v[80:95]
	v_exp_f32_e32 v102, v102
	v_exp_f32_e32 v103, v103
	v_add_f32_e32 v203, v203, v96
	s_waitcnt lgkmcnt(9)
	v_mfma_f32_32x32x16_bf16 v[80:95], v[216:219], v[124:127], v[80:95]
	v_add_f32_e32 v203, v203, v97
	v_add_f32_e32 v203, v203, v98
	v_add_f32_e32 v203, v203, v99
	v_add_f32_e32 v203, v203, v100
	v_add_f32_e32 v203, v203, v101
	s_waitcnt lgkmcnt(8)
	v_mfma_f32_32x32x16_bf16 v[80:95], v[220:223], v[128:131], v[80:95]
	v_add_f32_e32 v203, v203, v102
	v_add_f32_e32 v203, v203, v103
	v_cvt_pk_bf16_f32 v96, v96, v97
	v_cvt_pk_bf16_f32 v97, v98, v99
	v_cvt_pk_bf16_f32 v98, v100, v101
	s_waitcnt lgkmcnt(7)
	v_mfma_f32_32x32x16_bf16 v[80:95], v[224:227], v[132:135], v[80:95]
	v_cvt_pk_bf16_f32 v99, v102, v103
	v_exp_f32_e32 v104, v104
	v_exp_f32_e32 v105, v105
	s_waitcnt lgkmcnt(0)
	s_barrier
	v_mfma_f32_32x32x16_bf16 v[32:47], v[4:7], v[96:99], v[32:47]
	v_exp_f32_e32 v106, v106
	v_exp_f32_e32 v107, v107
	v_exp_f32_e32 v108, v108
	ds_read_b64 v[4:5], v202 offset:35392
	ds_read_b64 v[6:7], v202 offset:35408
	v_mfma_f32_32x32x16_bf16 v[16:31], v[8:11], v[96:99], v[16:31]
	v_exp_f32_e32 v109, v109
	v_exp_f32_e32 v110, v110
	v_exp_f32_e32 v111, v111
	ds_read_b64 v[8:9], v202 offset:39744
	ds_read_b64 v[10:11], v202 offset:39760
	v_add_f32_e32 v203, v203, v104
	v_add_f32_e32 v203, v203, v105
	v_add_f32_e32 v203, v203, v106
	v_add_f32_e32 v203, v203, v107
	v_add_f32_e32 v203, v203, v108
	v_add_f32_e32 v203, v203, v109
	v_add_f32_e32 v203, v203, v110
	v_add_f32_e32 v203, v203, v111
	v_cvt_pk_bf16_f32 v104, v104, v105
	v_cvt_pk_bf16_f32 v105, v106, v107
	v_cvt_pk_bf16_f32 v106, v108, v109
	v_cvt_pk_bf16_f32 v107, v110, v111
	s_nop 1
	v_mfma_f32_32x32x16_bf16 v[32:47], v[12:15], v[104:107], v[32:47]
	s_cmp_eq_u32 s9, 0
	s_cbranch_scc1 .Lattn_11_A_nosub
	v_sub_f32_e32 v80, v80, v2
	v_sub_f32_e32 v81, v81, v2
	v_sub_f32_e32 v82, v82, v2
	v_sub_f32_e32 v83, v83, v2
	v_sub_f32_e32 v84, v84, v2
	v_sub_f32_e32 v85, v85, v2
	v_sub_f32_e32 v86, v86, v2
	v_sub_f32_e32 v87, v87, v2
	v_sub_f32_e32 v88, v88, v2
	v_sub_f32_e32 v89, v89, v2
	v_sub_f32_e32 v90, v90, v2
	v_sub_f32_e32 v91, v91, v2
	v_sub_f32_e32 v92, v92, v2
	v_sub_f32_e32 v93, v93, v2
	v_sub_f32_e32 v94, v94, v2
	v_sub_f32_e32 v95, v95, v2
.Lattn_11_A_nosub:
	v_max3_f32 v185, v80, v81, v82
	v_max3_f32 v185, v185, v83, v84
	v_max3_f32 v185, v185, v85, v86
	v_max3_f32 v185, v185, v87, v88
	ds_read_b64 v[12:13], v202 offset:35424
	ds_read_b64 v[14:15], v202 offset:35440
	v_mfma_f32_32x32x16_bf16 v[16:31], v[192:195], v[104:107], v[16:31]
	v_max3_f32 v185, v185, v89, v90
	v_max3_f32 v185, v185, v91, v92
	v_max3_f32 v185, v185, v93, v94
	v_max_f32_e32 v185, v185, v95
	v_cmp_lt_f32_e32 vcc, s33, v185
	s_cbranch_vccnz .Lattn_11_A_rare
.Lattn_11_A_back:
	ds_read_b64 v[192:193], v202 offset:39776
	ds_read_b64 v[194:195], v202 offset:39792
	v_mfma_f32_32x32x16_bf16 v[96:111], v[204:207], v[228:231], 0
	v_exp_f32_e32 v80, v80
	v_exp_f32_e32 v81, v81
	v_exp_f32_e32 v82, v82
	ds_read_b128 v[204:207], v159 offset:44032
	v_mfma_f32_32x32x16_bf16 v[96:111], v[208:211], v[232:235], v[96:111]
	v_exp_f32_e32 v83, v83
	v_exp_f32_e32 v84, v84
	v_exp_f32_e32 v85, v85
	ds_read_b128 v[208:211], v159 offset:44064
	v_mfma_f32_32x32x16_bf16 v[96:111], v[212:215], v[236:239], v[96:111]
	v_exp_f32_e32 v86, v86
	v_exp_f32_e32 v87, v87
	v_add_f32_e32 v0, v0, v80
	ds_read_b128 v[212:215], v159 offset:44096
	v_mfma_f32_32x32x16_bf16 v[96:111], v[216:219], v[240:243], v[96:111]
	v_add_f32_e32 v0, v0, v81
	v_add_f32_e32 v0, v0, v82
	v_add_f32_e32 v0, v0, v83
	v_add_f32_e32 v0, v0, v84
	v_add_f32_e32 v0, v0, v85
	ds_read_b128 v[216:219], v159 offset:44128
	v_mfma_f32_32x32x16_bf16 v[96:111], v[220:223], v[244:247], v[96:111]
	v_add_f32_e32 v0, v0, v86
	v_add_f32_e32 v0, v0, v87
	v_cvt_pk_bf16_f32 v80, v80, v81
	v_cvt_pk_bf16_f32 v81, v82, v83
	v_cvt_pk_bf16_f32 v82, v84, v85
	ds_read_b128 v[220:223], v159 offset:44160
	v_mfma_f32_32x32x16_bf16 v[96:111], v[224:227], v[248:251], v[96:111]
	v_cvt_pk_bf16_f32 v83, v86, v87
	v_exp_f32_e32 v88, v88
	v_exp_f32_e32 v89, v89
	ds_read_b128 v[224:227], v159 offset:44192
	s_waitcnt lgkmcnt(12)
	v_mfma_f32_32x32x16_bf16 v[64:79], v[4:7], v[80:83], v[64:79]
	v_exp_f32_e32 v90, v90
	v_exp_f32_e32 v91, v91
	v_exp_f32_e32 v92, v92
	s_waitcnt lgkmcnt(10)
	v_mfma_f32_32x32x16_bf16 v[48:63], v[8:11], v[80:83], v[48:63]
	v_exp_f32_e32 v93, v93
	v_exp_f32_e32 v94, v94
	v_exp_f32_e32 v95, v95
	s_waitcnt lgkmcnt(8)
	v_add_f32_e32 v0, v0, v88
	v_add_f32_e32 v0, v0, v89
	v_add_f32_e32 v0, v0, v90
	v_add_f32_e32 v0, v0, v91
	v_add_f32_e32 v0, v0, v92
	v_add_f32_e32 v0, v0, v93
	v_add_f32_e32 v0, v0, v94
	v_add_f32_e32 v0, v0, v95
	v_cvt_pk_bf16_f32 v88, v88, v89
	v_cvt_pk_bf16_f32 v89, v90, v91
	v_cvt_pk_bf16_f32 v90, v92, v93
	v_cvt_pk_bf16_f32 v91, v94, v95
	s_nop 1
	v_mfma_f32_32x32x16_bf16 v[64:79], v[12:15], v[88:91], v[64:79]
	s_cmp_eq_u32 s12, 0
	s_cbranch_scc1 .Lattn_11_B_nosub
	v_sub_f32_e32 v96, v96, v201
	v_sub_f32_e32 v97, v97, v201
	v_sub_f32_e32 v98, v98, v201
	v_sub_f32_e32 v99, v99, v201
	v_sub_f32_e32 v100, v100, v201
	v_sub_f32_e32 v101, v101, v201
	v_sub_f32_e32 v102, v102, v201
	v_sub_f32_e32 v103, v103, v201
	v_sub_f32_e32 v104, v104, v201
	v_sub_f32_e32 v105, v105, v201
	v_sub_f32_e32 v106, v106, v201
	v_sub_f32_e32 v107, v107, v201
	v_sub_f32_e32 v108, v108, v201
	v_sub_f32_e32 v109, v109, v201
	v_sub_f32_e32 v110, v110, v201
	v_sub_f32_e32 v111, v111, v201

; #define MFMA32(a, b, c) __builtin_amdgcn_mfma_f32_32x32x16_bf16((a), (b), (c), 0, 0, 0)
; DI void attn_item(const Ctx& c, int item, bf16* lds) {
;     ...
;         for (int mt = 0; mt < 2; ++mt)
; #pragma unroll
;           for (int s = 0; s < 6; ++s) {
;             const bf16x8 a = *(const bf16x8*)(Ks + (32 * mt + r) * AK_LD + 16 * s + 8 * hh);
;             const bf16x8 qb_ = (qs == 0) ? qf0[s] : *(const bf16x8*)(Qs + r * AK_LD + 16 * s + 8 * hh);
;             st[mt] = (s == 0) ? MFMA32(a, qb_, zz) : MFMA32(a, qb_, st[mt]);
;           }
;       }
;       if (__builtin_amdgcn_ballot_w64(m[qs] != 0.f) != 0ull) {
; #pragma unroll
;         for (int i = 0; i < 16; ++i) { st[0][i] -= m[qs]; st[1][i] -= m[qs]; }
;       }
;       float mx = st[0][0];
; #pragma unroll
;       for (int i = 1; i < 16; ++i) mx = fmaxf(mx, st[0][i]);
; #pragma unroll
;       for (int i = 0; i < 16; ++i) mx = fmaxf(mx, st[1][i]);
;       mx = xhalf_max(mx);
;       if (__builtin_amdgcn_ballot_w64((kt == 0) ? (fabsf(mx) > 16.f) : (mx > 16.f)) != 0ull) {
;         const float d = (kt == 0) ? mx : fmaxf(mx, 0.f);
;         const float alpha = __builtin_amdgcn_exp2f(-d);
;         m[qs] += d; lsum[qs] *= alpha;
; #pragma unroll
;         for (int i = 0; i < 16; ++i) { ot[qs][0][i] *= alpha; ot[qs][1][i] *= alpha; st[0][i] -= d; st[1][i] -= d; }
;       }
;       float ps = 0.f;
; #pragma unroll
;       for (int sp = 0; sp < 4; ++sp) {
;         const int mt = sp >> 1, s2 = sp & 1;
;         float e[8];
; #pragma unroll
;         for (int j = 0; j < 8; ++j) { e[j] = __builtin_amdgcn_exp2f(st[mt][8 * s2 + j]); ps += e[j]; }
;         u32x4 pk;
;         pk[0] = pk2(e[0], e[1]); pk[1] = pk2(e[2], e[3]); pk[2] = pk2(e[4], e[5]); pk[3] = pk2(e[6], e[7]);
;         const bf16x8 pf = __builtin_bit_cast(bf16x8, pk);
; #pragma unroll
;         for (int vt = 0; vt < 2; ++vt) {
;           const bf16* vp = Vs + (32 * vt + r) * AV_LD + 32 * mt + 16 * s2 + 4 * hh;
;           const s16x4 lo = *(const s16x4*)(vp), hi = *(const s16x4*)(vp + 8);
;           const bf16x8 a = __builtin_shufflevector(lo, hi, 0, 1, 2, 3, 4, 5, 6, 7);
;           ot[qs][vt] = MFMA32(a, pf, ot[qs][vt]);
;         }
;       }
;       lsum[qs] += ps;
.Lattn_11_B_back:
	s_waitcnt lgkmcnt(5)
	v_mfma_f32_32x32x16_bf16 v[80:95], v[204:207], v[112:115], 0
	v_exp_f32_e32 v96, v96
	v_exp_f32_e32 v97, v97
	v_exp_f32_e32 v98, v98
	s_waitcnt lgkmcnt(4)
	v_mfma_f32_32x32x16_bf16 v[80:95], v[208:211], v[116:119], v[80:95]
	v_exp_f32_e32 v99, v99
	v_exp_f32_e32 v100, v100
	v_exp_f32_e32 v101, v101
	s_waitcnt lgkmcnt(3)
	v_mfma_f32_32x32x16_bf16 v[80:95], v[212:215], v[120:123], v[80:95]
	v_exp_f32_e32 v102, v102
	v_exp_f32_e32 v103, v103
	v_add_f32_e32 v203, v203, v96
	s_waitcnt lgkmcnt(2)
	v_mfma_f32_32x32x16_bf16 v[80:95], v[216:219], v[124:127], v[80:95]
	v_add_f32_e32 v203, v203, v97
	v_add_f32_e32 v203, v203, v98
	v_add_f32_e32 v203, v203, v99
	v_add_f32_e32 v203, v203, v100
	v_add_f32_e32 v203, v203, v101
	s_waitcnt lgkmcnt(1)
	v_mfma_f32_32x32x16_bf16 v[80:95], v[220:223], v[128:131], v[80:95]
	v_add_f32_e32 v203, v203, v102
	v_add_f32_e32 v203, v203, v103
	v_cvt_pk_bf16_f32 v96, v96, v97
	v_cvt_pk_bf16_f32 v97, v98, v99
	v_cvt_pk_bf16_f32 v98, v100, v101
	s_waitcnt lgkmcnt(0)
	v_mfma_f32_32x32x16_bf16 v[80:95], v[224:227], v[132:135], v[80:95]
	v_cvt_pk_bf16_f32 v99, v102, v103
	v_exp_f32_e32 v104, v104
	v_exp_f32_e32 v105, v105
	s_add_i32 s1, s1, 1
	v_mfma_f32_32x32x16_bf16 v[32:47], v[4:7], v[96:99], v[32:47]
	v_exp_f32_e32 v106, v106
	v_exp_f32_e32 v107, v107
	v_exp_f32_e32 v108, v108
	ds_read_b64 v[4:5], v202 offset:57344
	ds_read_b64 v[6:7], v202 offset:57360
	v_mfma_f32_32x32x16_bf16 v[16:31], v[8:11], v[96:99], v[16:31]
	v_exp_f32_e32 v109, v109
	v_exp_f32_e32 v110, v110
	v_exp_f32_e32 v111, v111
	ds_read_b64 v[8:9], v202 offset:61696
	ds_read_b64 v[10:11], v202 offset:61712
	v_add_f32_e32 v203, v203, v104
	v_add_f32_e32 v203, v203, v105
	v_add_f32_e32 v203, v203, v106
	v_add_f32_e32 v203, v203, v107
	v_add_f32_e32 v203, v203, v108
	v_add_f32_e32 v203, v203, v109
	v_add_f32_e32 v203, v203, v110
	v_add_f32_e32 v203, v203, v111
	v_cvt_pk_bf16_f32 v104, v104, v105
	v_cvt_pk_bf16_f32 v105, v106, v107
	v_cvt_pk_bf16_f32 v106, v108, v109
	v_cvt_pk_bf16_f32 v107, v110, v111
	s_nop 1
	v_mfma_f32_32x32x16_bf16 v[32:47], v[12:15], v[104:107], v[32:47]
	s_cmp_eq_u32 s9, 0
	s_cbranch_scc1 .Lattn_20_A_nosub
	v_sub_f32_e32 v80, v80, v2
	v_sub_f32_e32 v81, v81, v2
	v_sub_f32_e32 v82, v82, v2
	v_sub_f32_e32 v83, v83, v2
	v_sub_f32_e32 v84, v84, v2
	v_sub_f32_e32 v85, v85, v2
	v_sub_f32_e32 v86, v86, v2
	v_sub_f32_e32 v87, v87, v2
	v_sub_f32_e32 v88, v88, v2
	v_sub_f32_e32 v89, v89, v2
	v_sub_f32_e32 v90, v90, v2
	v_sub_f32_e32 v91, v91, v2
	v_sub_f32_e32 v92, v92, v2
	v_sub_f32_e32 v93, v93, v2
	v_sub_f32_e32 v94, v94, v2
	v_sub_f32_e32 v95, v95, v2
.Lattn_20_A_nosub:
	v_max3_f32 v185, v80, v81, v82
	v_max3_f32 v185, v185, v83, v84
	v_max3_f32 v185, v185, v85, v86
	v_max3_f32 v185, v185, v87, v88
	ds_read_b64 v[12:13], v202 offset:57376
	ds_read_b64 v[14:15], v202 offset:57392
	v_mfma_f32_32x32x16_bf16 v[16:31], v[192:195], v[104:107], v[16:31]
	v_max3_f32 v185, v185, v89, v90
	v_max3_f32 v185, v185, v91, v92
	v_max3_f32 v185, v185, v93, v94
	v_max_f32_e32 v185, v185, v95
	v_cmp_lt_f32_e32 vcc, s33, v185
	s_cbranch_vccnz .Lattn_20_A_rare
.Lattn_20_A_back:
	ds_read_b64 v[192:193], v202 offset:61728
	ds_read_b64 v[194:195], v202 offset:61744
	v_mfma_f32_32x32x16_bf16 v[96:111], v[204:207], v[228:231], 0
	v_exp_f32_e32 v80, v80
	v_exp_f32_e32 v81, v81
	v_exp_f32_e32 v82, v82
	ds_read_b128 v[204:207], v159 offset:50688
	v_mfma_f32_32x32x16_bf16 v[96:111], v[208:211], v[232:235], v[96:111]
	v_exp_f32_e32 v83, v83
	v_exp_f32_e32 v84, v84
	v_exp_f32_e32 v85, v85
	ds_read_b128 v[208:211], v159 offset:50720
	v_mfma_f32_32x32x16_bf16 v[96:111], v[212:215], v[236:239], v[96:111]
	v_exp_f32_e32 v86, v86
	v_exp_f32_e32 v87, v87
	v_add_f32_e32 v0, v0, v80
	ds_read_b128 v[212:215], v159 offset:50752
	v_mfma_f32_32x32x16_bf16 v[96:111], v[216:219], v[240:243], v[96:111]
	v_add_f32_e32 v0, v0, v81
	v_add_f32_e32 v0, v0, v82
	v_add_f32_e32 v0, v0, v83
	v_add_f32_e32 v0, v0, v84
	v_add_f32_e32 v0, v0, v85
	ds_read_b128 v[216:219], v159 offset:50784
	v_mfma_f32_32x32x16_bf16 v[96:111], v[220:223], v[244:247], v[96:111]
	v_add_f32_e32 v0, v0, v86
	v_add_f32_e32 v0, v0, v87
	v_cvt_pk_bf16_f32 v80, v80, v81
	v_cvt_pk_bf16_f32 v81, v82, v83
	v_cvt_pk_bf16_f32 v82, v84, v85
	ds_read_b128 v[220:223], v159 offset:50816
	v_mfma_f32_32x32x16_bf16 v[96:111], v[224:227], v[248:251], v[96:111]
	v_cvt_pk_bf16_f32 v83, v86, v87
	v_exp_f32_e32 v88, v88
	v_exp_f32_e32 v89, v89
	ds_read_b128 v[224:227], v159 offset:50848
	s_waitcnt lgkmcnt(12)
	v_mfma_f32_32x32x16_bf16 v[64:79], v[4:7], v[80:83], v[64:79]
	v_exp_f32_e32 v90, v90
	v_exp_f32_e32 v91, v91
	v_exp_f32_e32 v92, v92
	s_waitcnt vmcnt(0)
	ds_write_b128 v3, v[136:139] offset:0
	s_waitcnt lgkmcnt(11)
	v_mfma_f32_32x32x16_bf16 v[48:63], v[8:11], v[80:83], v[48:63]
	v_exp_f32_e32 v93, v93
	v_exp_f32_e32 v94, v94
	v_exp_f32_e32 v95, v95
	ds_write_b128 v161, v[140:143] offset:0
	s_waitcnt lgkmcnt(10)
	v_add_f32_e32 v0, v0, v88
	v_add_f32_e32 v0, v0, v89
	v_add_f32_e32 v0, v0, v90
	v_add_f32_e32 v0, v0, v91
	v_add_f32_e32 v0, v0, v92
	v_add_f32_e32 v0, v0, v93
	v_add_f32_e32 v0, v0, v94
	v_add_f32_e32 v0, v0, v95
	v_cvt_pk_bf16_f32 v88, v88, v89
	v_cvt_pk_bf16_f32 v89, v90, v91
	v_cvt_pk_bf16_f32 v90, v92, v93
	v_cvt_pk_bf16_f32 v91, v94, v95
	s_nop 1
	v_mfma_f32_32x32x16_bf16 v[64:79], v[12:15], v[88:91], v[64:79]
	s_cmp_eq_u32 s12, 0
	s_cbranch_scc1 .Lattn_20_B_nosub
	v_sub_f32_e32 v96, v96, v201
	v_sub_f32_e32 v97, v97, v201
	v_sub_f32_e32 v98, v98, v201
	v_sub_f32_e32 v99, v99, v201
	v_sub_f32_e32 v100, v100, v201
	v_sub_f32_e32 v101, v101, v201
	v_sub_f32_e32 v102, v102, v201
	v_sub_f32_e32 v103, v103, v201
	v_sub_f32_e32 v104, v104, v201
	v_sub_f32_e32 v105, v105, v201
	v_sub_f32_e32 v106, v106, v201
	v_sub_f32_e32 v107, v107, v201
	v_sub_f32_e32 v108, v108, v201
	v_sub_f32_e32 v109, v109, v201
	v_sub_f32_e32 v110, v110, v201
	v_sub_f32_e32 v111, v111, v201
; #define MFMA32(a, b, c) __builtin_amdgcn_mfma_f32_32x32x16_bf16((a), (b), (c), 0, 0, 0)
; DI void attn_item(const Ctx& c, int item, bf16* lds) {
;     ...
;         for (int mt = 0; mt < 2; ++mt)
; #pragma unroll
;           for (int s = 0; s < 6; ++s) {
;             const bf16x8 a = *(const bf16x8*)(Ks + (32 * mt + r) * AK_LD + 16 * s + 8 * hh);
;             const bf16x8 qb_ = (qs == 0) ? qf0[s] : *(const bf16x8*)(Qs + r * AK_LD + 16 * s + 8 * hh);
;             st[mt] = (s == 0) ? MFMA32(a, qb_, zz) : MFMA32(a, qb_, st[mt]);
;           }
;       }
;       if (__builtin_amdgcn_ballot_w64(m[qs] != 0.f) != 0ull) {
; #pragma unroll
;         for (int i = 0; i < 16; ++i) { st[0][i] -= m[qs]; st[1][i] -= m[qs]; }
;       }
;       float mx = st[0][0];
; #pragma unroll
;       for (int i = 1; i < 16; ++i) mx = fmaxf(mx, st[0][i]);
; #pragma unroll
;       for (int i = 0; i < 16; ++i) mx = fmaxf(mx, st[1][i]);
;       mx = xhalf_max(mx);
;       if (__builtin_amdgcn_ballot_w64((kt == 0) ? (fabsf(mx) > 16.f) : (mx > 16.f)) != 0ull) {
;         const float d = (kt == 0) ? mx : fmaxf(mx, 0.f);
;         const float alpha = __builtin_amdgcn_exp2f(-d);
;         m[qs] += d; lsum[qs] *= alpha;
; #pragma unroll
;         for (int i = 0; i < 16; ++i) { ot[qs][0][i] *= alpha; ot[qs][1][i] *= alpha; st[0][i] -= d; st[1][i] -= d; }
;       }
;       float ps = 0.f;
; #pragma unroll
;       for (int sp = 0; sp < 4; ++sp) {
;         const int mt = sp >> 1, s2 = sp & 1;
;         float e[8];
; #pragma unroll
;         for (int j = 0; j < 8; ++j) { e[j] = __builtin_amdgcn_exp2f(st[mt][8 * s2 + j]); ps += e[j]; }
;         u32x4 pk;
;         pk[0] = pk2(e[0], e[1]); pk[1] = pk2(e[2], e[3]); pk[2] = pk2(e[4], e[5]); pk[3] = pk2(e[6], e[7]);
;         const bf16x8 pf = __builtin_bit_cast(bf16x8, pk);
; #pragma unroll
;         for (int vt = 0; vt < 2; ++vt) {
;           const bf16* vp = Vs + (32 * vt + r) * AV_LD + 32 * mt + 16 * s2 + 4 * hh;
;           const s16x4 lo = *(const s16x4*)(vp), hi = *(const s16x4*)(vp + 8);
;           const bf16x8 a = __builtin_shufflevector(lo, hi, 0, 1, 2, 3, 4, 5, 6, 7);
;           ot[qs][vt] = MFMA32(a, pf, ot[qs][vt]);
;         }
;       }
;       lsum[qs] += ps;
.Lattn_20_B_nosub:
	v_max3_f32 v185, v96, v97, v98
	v_max3_f32 v185, v185, v99, v100
	v_max3_f32 v185, v185, v101, v102
	v_max3_f32 v185, v185, v103, v104
	ds_write_b128 v182, v[144:147] offset:0
	s_waitcnt lgkmcnt(9)
	v_mfma_f32_32x32x16_bf16 v[48:63], v[192:195], v[88:91], v[48:63]
	v_max3_f32 v185, v185, v105, v106
	v_max3_f32 v185, v185, v107, v108
	v_max3_f32 v185, v185, v109, v110
	v_max_f32_e32 v185, v185, v111
	v_cmp_lt_f32_e32 vcc, s33, v185
	s_cbranch_vccnz .Lattn_20_B_rare
.Lattn_20_B_back:
	ds_write_b64 v184, v[148:149] offset:13312
	ds_write_b64 v184, v[150:151] offset:13320
	s_waitcnt lgkmcnt(10)
	v_mfma_f32_32x32x16_bf16 v[80:95], v[204:207], v[112:115], 0
	v_exp_f32_e32 v96, v96
	v_exp_f32_e32 v97, v97
	v_exp_f32_e32 v98, v98
	ds_write_b64 v184, v[152:153] offset:17664
	ds_write_b64 v184, v[154:155] offset:17672
	s_waitcnt lgkmcnt(11)
	v_mfma_f32_32x32x16_bf16 v[80:95], v[208:211], v[116:119], v[80:95]
	v_exp_f32_e32 v99, v99
	v_exp_f32_e32 v100, v100
	v_exp_f32_e32 v101, v101
	global_load_dwordx4 v[136:139], v166, s[10:11]
	global_load_dwordx4 v[140:143], v168, s[10:11]
	global_load_dwordx4 v[144:147], v170, s[10:11]
	global_load_dwordx4 v[148:151], v162, s[2:3]
	global_load_dwordx4 v[152:155], v164, s[2:3]
	s_add_u32 s10, s10, 0x3000
	s_addc_u32 s11, s11, 0
	s_add_u32 s2, s2, 0x80
	s_addc_u32 s3, s3, 0
	s_waitcnt lgkmcnt(10)
	v_mfma_f32_32x32x16_bf16 v[80:95], v[212:215], v[120:123], v[80:95]
	v_exp_f32_e32 v102, v102
	v_exp_f32_e32 v103, v103
	v_add_f32_e32 v203, v203, v96
	s_waitcnt lgkmcnt(9)
	v_mfma_f32_32x32x16_bf16 v[80:95], v[216:219], v[124:127], v[80:95]
	v_add_f32_e32 v203, v203, v97
	v_add_f32_e32 v203, v203, v98
	v_add_f32_e32 v203, v203, v99
	v_add_f32_e32 v203, v203, v100
	v_add_f32_e32 v203, v203, v101
	s_waitcnt lgkmcnt(8)
	v_mfma_f32_32x32x16_bf16 v[80:95], v[220:223], v[128:131], v[80:95]
	v_add_f32_e32 v203, v203, v102
	v_add_f32_e32 v203, v203, v103
	v_cvt_pk_bf16_f32 v96, v96, v97
	v_cvt_pk_bf16_f32 v97, v98, v99
	v_cvt_pk_bf16_f32 v98, v100, v101
	s_waitcnt lgkmcnt(7)
	v_mfma_f32_32x32x16_bf16 v[80:95], v[224:227], v[132:135], v[80:95]
	v_cvt_pk_bf16_f32 v99, v102, v103
	v_exp_f32_e32 v104, v104
	v_exp_f32_e32 v105, v105
	s_waitcnt lgkmcnt(0)
	s_barrier
	v_mfma_f32_32x32x16_bf16 v[32:47], v[4:7], v[96:99], v[32:47]
	v_exp_f32_e32 v106, v106
	v_exp_f32_e32 v107, v107
	v_exp_f32_e32 v108, v108
	ds_read_b64 v[4:5], v202 offset:57408
	ds_read_b64 v[6:7], v202 offset:57424
	v_mfma_f32_32x32x16_bf16 v[16:31], v[8:11], v[96:99], v[16:31]
	v_exp_f32_e32 v109, v109
	v_exp_f32_e32 v110, v110
	v_exp_f32_e32 v111, v111
	ds_read_b64 v[8:9], v202 offset:61760
	ds_read_b64 v[10:11], v202 offset:61776
	v_add_f32_e32 v203, v203, v104
	v_add_f32_e32 v203, v203, v105
	v_add_f32_e32 v203, v203, v106
	v_add_f32_e32 v203, v203, v107
	v_add_f32_e32 v203, v203, v108
	v_add_f32_e32 v203, v203, v109
	v_add_f32_e32 v203, v203, v110
	v_add_f32_e32 v203, v203, v111
	v_cvt_pk_bf16_f32 v104, v104, v105
	v_cvt_pk_bf16_f32 v105, v106, v107
	v_cvt_pk_bf16_f32 v106, v108, v109
	v_cvt_pk_bf16_f32 v107, v110, v111
	s_nop 1
	v_mfma_f32_32x32x16_bf16 v[32:47], v[12:15], v[104:107], v[32:47]
	s_cmp_eq_u32 s9, 0
	s_cbranch_scc1 .Lattn_21_A_nosub
	v_sub_f32_e32 v80, v80, v2
	v_sub_f32_e32 v81, v81, v2
	v_sub_f32_e32 v82, v82, v2
	v_sub_f32_e32 v83, v83, v2
	v_sub_f32_e32 v84, v84, v2
	v_sub_f32_e32 v85, v85, v2
	v_sub_f32_e32 v86, v86, v2
	v_sub_f32_e32 v87, v87, v2
	v_sub_f32_e32 v88, v88, v2
	v_sub_f32_e32 v89, v89, v2
	v_sub_f32_e32 v90, v90, v2
	v_sub_f32_e32 v91, v91, v2
	v_sub_f32_e32 v92, v92, v2
	v_sub_f32_e32 v93, v93, v2
	v_sub_f32_e32 v94, v94, v2
	v_sub_f32_e32 v95, v95, v2
.Lattn_21_A_nosub:
	v_max3_f32 v185, v80, v81, v82
	v_max3_f32 v185, v185, v83, v84
	v_max3_f32 v185, v185, v85, v86
	v_max3_f32 v185, v185, v87, v88
	ds_read_b64 v[12:13], v202 offset:57440
	ds_read_b64 v[14:15], v202 offset:57456
	v_mfma_f32_32x32x16_bf16 v[16:31], v[192:195], v[104:107], v[16:31]
	v_max3_f32 v185, v185, v89, v90
	v_max3_f32 v185, v185, v91, v92
	v_max3_f32 v185, v185, v93, v94
	v_max_f32_e32 v185, v185, v95
	v_cmp_lt_f32_e32 vcc, s33, v185
	s_cbranch_vccnz .Lattn_21_A_rare
.Lattn_21_A_back:
	ds_read_b64 v[192:193], v202 offset:61792
	ds_read_b64 v[194:195], v202 offset:61808
	v_mfma_f32_32x32x16_bf16 v[96:111], v[204:207], v[228:231], 0
	v_exp_f32_e32 v80, v80
	v_exp_f32_e32 v81, v81
	v_exp_f32_e32 v82, v82
	ds_read_b128 v[204:207], v159 offset:0
	v_mfma_f32_32x32x16_bf16 v[96:111], v[208:211], v[232:235], v[96:111]
	v_exp_f32_e32 v83, v83
	v_exp_f32_e32 v84, v84
	v_exp_f32_e32 v85, v85
	ds_read_b128 v[208:211], v159 offset:32
	v_mfma_f32_32x32x16_bf16 v[96:111], v[212:215], v[236:239], v[96:111]
	v_exp_f32_e32 v86, v86
	v_exp_f32_e32 v87, v87
	v_add_f32_e32 v0, v0, v80
	ds_read_b128 v[212:215], v159 offset:64
	v_mfma_f32_32x32x16_bf16 v[96:111], v[216:219], v[240:243], v[96:111]
	v_add_f32_e32 v0, v0, v81
	v_add_f32_e32 v0, v0, v82
	v_add_f32_e32 v0, v0, v83
	v_add_f32_e32 v0, v0, v84
	v_add_f32_e32 v0, v0, v85
	ds_read_b128 v[216:219], v159 offset:96
	v_mfma_f32_32x32x16_bf16 v[96:111], v[220:223], v[244:247], v[96:111]
	v_add_f32_e32 v0, v0, v86
	v_add_f32_e32 v0, v0, v87
	v_cvt_pk_bf16_f32 v80, v80, v81
	v_cvt_pk_bf16_f32 v81, v82, v83
	v_cvt_pk_bf16_f32 v82, v84, v85
	ds_read_b128 v[220:223], v159 offset:128
	v_mfma_f32_32x32x16_bf16 v[96:111], v[224:227], v[248:251], v[96:111]
	v_cvt_pk_bf16_f32 v83, v86, v87
	v_exp_f32_e32 v88, v88
	v_exp_f32_e32 v89, v89
	ds_read_b128 v[224:227], v159 offset:160
	s_waitcnt lgkmcnt(12)
	v_mfma_f32_32x32x16_bf16 v[64:79], v[4:7], v[80:83], v[64:79]
	v_exp_f32_e32 v90, v90
	v_exp_f32_e32 v91, v91
	v_exp_f32_e32 v92, v92
	s_waitcnt lgkmcnt(10)
	v_mfma_f32_32x32x16_bf16 v[48:63], v[8:11], v[80:83], v[48:63]
	v_exp_f32_e32 v93, v93
	v_exp_f32_e32 v94, v94
	v_exp_f32_e32 v95, v95
	s_waitcnt lgkmcnt(8)
	v_add_f32_e32 v0, v0, v88
	v_add_f32_e32 v0, v0, v89
	v_add_f32_e32 v0, v0, v90
	v_add_f32_e32 v0, v0, v91
	v_add_f32_e32 v0, v0, v92
	v_add_f32_e32 v0, v0, v93
	v_add_f32_e32 v0, v0, v94
	v_add_f32_e32 v0, v0, v95
	v_cvt_pk_bf16_f32 v88, v88, v89
	v_cvt_pk_bf16_f32 v89, v90, v91
	v_cvt_pk_bf16_f32 v90, v92, v93
	v_cvt_pk_bf16_f32 v91, v94, v95
	s_nop 1
	v_mfma_f32_32x32x16_bf16 v[64:79], v[12:15], v[88:91], v[64:79]
	s_cmp_eq_u32 s12, 0
	s_cbranch_scc1 .Lattn_21_B_nosub
	v_sub_f32_e32 v96, v96, v201
	v_sub_f32_e32 v97, v97, v201
	v_sub_f32_e32 v98, v98, v201
	v_sub_f32_e32 v99, v99, v201
	v_sub_f32_e32 v100, v100, v201
	v_sub_f32_e32 v101, v101, v201
	v_sub_f32_e32 v102, v102, v201
	v_sub_f32_e32 v103, v103, v201
	v_sub_f32_e32 v104, v104, v201
	v_sub_f32_e32 v105, v105, v201
	v_sub_f32_e32 v106, v106, v201
	v_sub_f32_e32 v107, v107, v201
	v_sub_f32_e32 v108, v108, v201
	v_sub_f32_e32 v109, v109, v201
	v_sub_f32_e32 v110, v110, v201
	v_sub_f32_e32 v111, v111, v201

; #define MFMA32(a, b, c) __builtin_amdgcn_mfma_f32_32x32x16_bf16((a), (b), (c), 0, 0, 0)
; DI void attn_item(const Ctx& c, int item, bf16* lds) {
;     ...
;       float ps = 0.f;
; #pragma unroll
;       for (int sp = 0; sp < 4; ++sp) {
;         const int mt = sp >> 1, s2 = sp & 1;
;         float e[8];
; #pragma unroll
;         for (int j = 0; j < 8; ++j) { e[j] = __builtin_amdgcn_exp2f(st[mt][8 * s2 + j]); ps += e[j]; }
;         u32x4 pk;
;         pk[0] = pk2(e[0], e[1]); pk[1] = pk2(e[2], e[3]); pk[2] = pk2(e[4], e[5]); pk[3] = pk2(e[6], e[7]);
;         const bf16x8 pf = __builtin_bit_cast(bf16x8, pk);
; #pragma unroll
;         for (int vt = 0; vt < 2; ++vt) {
;           const bf16* vp = Vs + (32 * vt + r) * AV_LD + 32 * mt + 16 * s2 + 4 * hh;
;           const s16x4 lo = *(const s16x4*)(vp), hi = *(const s16x4*)(vp + 8);
;           const bf16x8 a = __builtin_shufflevector(lo, hi, 0, 1, 2, 3, 4, 5, 6, 7);
;           ot[qs][vt] = MFMA32(a, pf, ot[qs][vt]);
;         }
;       }
;       lsum[qs] += ps;
;     }
;   }
.Lattn_21_B_back:
	s_waitcnt lgkmcnt(5)
	v_mfma_f32_32x32x16_bf16 v[80:95], v[204:207], v[112:115], 0
	v_exp_f32_e32 v96, v96
	v_exp_f32_e32 v97, v97
	v_exp_f32_e32 v98, v98
	s_waitcnt lgkmcnt(4)
	v_mfma_f32_32x32x16_bf16 v[80:95], v[208:211], v[116:119], v[80:95]
	v_exp_f32_e32 v99, v99
	v_exp_f32_e32 v100, v100
	v_exp_f32_e32 v101, v101
	s_waitcnt lgkmcnt(3)
	v_mfma_f32_32x32x16_bf16 v[80:95], v[212:215], v[120:123], v[80:95]
	v_exp_f32_e32 v102, v102
	v_exp_f32_e32 v103, v103
	v_add_f32_e32 v203, v203, v96
	s_waitcnt lgkmcnt(2)
	v_mfma_f32_32x32x16_bf16 v[80:95], v[216:219], v[124:127], v[80:95]
	v_add_f32_e32 v203, v203, v97
	v_add_f32_e32 v203, v203, v98
	v_add_f32_e32 v203, v203, v99
	v_add_f32_e32 v203, v203, v100
	v_add_f32_e32 v203, v203, v101
	s_waitcnt lgkmcnt(1)
	v_mfma_f32_32x32x16_bf16 v[80:95], v[220:223], v[128:131], v[80:95]
	v_add_f32_e32 v203, v203, v102
	v_add_f32_e32 v203, v203, v103
	v_cvt_pk_bf16_f32 v96, v96, v97
	v_cvt_pk_bf16_f32 v97, v98, v99
	v_cvt_pk_bf16_f32 v98, v100, v101
	s_waitcnt lgkmcnt(0)
	v_mfma_f32_32x32x16_bf16 v[80:95], v[224:227], v[132:135], v[80:95]
	v_cvt_pk_bf16_f32 v99, v102, v103
	v_exp_f32_e32 v104, v104
	v_exp_f32_e32 v105, v105
	s_add_i32 s1, s1, 1
	v_exp_f32_e32 v106, v106
	v_exp_f32_e32 v107, v107
	v_exp_f32_e32 v108, v108
	v_exp_f32_e32 v109, v109
	v_exp_f32_e32 v110, v110
	v_exp_f32_e32 v111, v111
	v_add_f32_e32 v203, v203, v104
	v_add_f32_e32 v203, v203, v105
	v_add_f32_e32 v203, v203, v106
	v_add_f32_e32 v203, v203, v107
	v_add_f32_e32 v203, v203, v108
	v_add_f32_e32 v203, v203, v109
	v_add_f32_e32 v203, v203, v110
	v_add_f32_e32 v203, v203, v111
	v_cvt_pk_bf16_f32 v104, v104, v105
	v_cvt_pk_bf16_f32 v105, v106, v107
	v_cvt_pk_bf16_f32 v106, v108, v109
	v_cvt_pk_bf16_f32 v107, v110, v111
	s_cmpk_lg_i32 s1, 0x84
	s_cbranch_scc1 .Lattn_loop
	v_mfma_f32_32x32x16_bf16 v[32:47], v[4:7], v[96:99], v[32:47]
	v_mfma_f32_32x32x16_bf16 v[16:31], v[8:11], v[96:99], v[16:31]
	v_mfma_f32_32x32x16_bf16 v[32:47], v[12:15], v[104:107], v[32:47]
	v_mfma_f32_32x32x16_bf16 v[16:31], v[192:195], v[104:107], v[16:31]
	v_mov_b32_e32 v8, v203
	s_setprio 0
	s_waitcnt vmcnt(0)
	s_branch .LBB0_820
